# comb13 + grid barrier: XCD leader issues its invalidate together with its L2 writeback (one wait), so the XCD generation bump is not queued behind it
# baseline (speedup 1.0000x reference)
; __device__ __forceinline__ unsigned xb_ld(unsigned* p)              { return __hip_atomic_load(p, __ATOMIC_RELAXED, __HIP_MEMORY_SCOPE_AGENT); }
; __device__ __forceinline__ unsigned xb_add(unsigned* p, unsigned v) { return __hip_atomic_fetch_add(p, v, __ATOMIC_RELAXED, __HIP_MEMORY_SCOPE_AGENT); }
; #define XB_SPIN(cond, bar) do { unsigned _sp = 0; while (cond) { __builtin_amdgcn_s_sleep(1); \
;     if ((++_sp & 255u) == 0u) { if (xb_ld(&(bar)[XB_TMO])) break; if (_sp > XB_SPIN_CAP) { atomicAdd(&(bar)[XB_TMO], 1u); break; } } } } while (0)
; __device__ __forceinline__ void xcd_barrier(const XcdBarrier& b) {
;     ...
;         if (old + 1u == (gen + 1u) * nloc) {
;             __builtin_amdgcn_fence(__ATOMIC_RELEASE, "agent");
;             asm volatile("s_waitcnt vmcnt(0)" ::: "memory");
;             const unsigned og = xb_add(&bar[XB_TOP], 1u);
;             const unsigned tg = og / nx;
;             if (og + 1u == (tg + 1u) * nx) xb_add(&bar[XB_TOPGEN], 1u);
;             else XB_SPIN(xb_ld(&bar[XB_TOPGEN]) == tg, bar);
;             __builtin_amdgcn_fence(__ATOMIC_ACQUIRE, "agent");
;             xb_add(&bar[XB_XGEN(b.x)], 1u);
.LBB0_117:
	s_andn2_saveexec_b64 s[6:7], s[6:7]
	s_cbranch_execz .LBB0_135
	s_mov_b64 s[6:7], exec
	buffer_wbl2 sc1
	buffer_inv sc1
	s_waitcnt lgkmcnt(0)
	s_waitcnt vmcnt(0)
	v_mbcnt_lo_u32_b32 v2, s6, 0
	v_mbcnt_hi_u32_b32 v2, s7, v2
	v_cmp_eq_u32_e32 vcc, 0, v2
	s_and_saveexec_b64 s[8:9], vcc
	s_cbranch_execz .LBB0_120
	s_bcnt1_i32_b64 s6, s[6:7]
	v_mov_b32_e32 v3, 0x3f52f000
	v_mov_b32_e32 v4, s6
	global_atomic_add v3, v3, v4, s[30:31] offset:1024 sc0

; __device__ __forceinline__ unsigned xb_ld(unsigned* p)              { return __hip_atomic_load(p, __ATOMIC_RELAXED, __HIP_MEMORY_SCOPE_AGENT); }
; __device__ __forceinline__ unsigned xb_add(unsigned* p, unsigned v) { return __hip_atomic_fetch_add(p, v, __ATOMIC_RELAXED, __HIP_MEMORY_SCOPE_AGENT); }
; #define XB_SPIN(cond, bar) do { unsigned _sp = 0; while (cond) { __builtin_amdgcn_s_sleep(1); \
;     if ((++_sp & 255u) == 0u) { if (xb_ld(&(bar)[XB_TMO])) break; if (_sp > XB_SPIN_CAP) { atomicAdd(&(bar)[XB_TMO], 1u); break; } } } } while (0)
; __device__ __forceinline__ void xcd_barrier(const XcdBarrier& b) {
;     ...
;         if (old + 1u == (gen + 1u) * nloc) {
;             __builtin_amdgcn_fence(__ATOMIC_RELEASE, "agent");
;             asm volatile("s_waitcnt vmcnt(0)" ::: "memory");
;             const unsigned og = xb_add(&bar[XB_TOP], 1u);
;             const unsigned tg = og / nx;
;             if (og + 1u == (tg + 1u) * nx) xb_add(&bar[XB_TOPGEN], 1u);
;             else XB_SPIN(xb_ld(&bar[XB_TOPGEN]) == tg, bar);
;             __builtin_amdgcn_fence(__ATOMIC_ACQUIRE, "agent");
;             xb_add(&bar[XB_XGEN(b.x)], 1u);
.LBB0_189:
	s_andn2_saveexec_b64 s[8:9], s[8:9]
	s_cbranch_execz .LBB0_207
	s_mov_b64 s[8:9], exec
	buffer_wbl2 sc1
	buffer_inv sc1
	s_waitcnt lgkmcnt(0)
	s_waitcnt vmcnt(0)
	v_mbcnt_lo_u32_b32 v3, s8, 0
	v_mbcnt_hi_u32_b32 v3, s9, v3
	v_cmp_eq_u32_e32 vcc, 0, v3
	s_and_saveexec_b64 s[10:11], vcc
	s_cbranch_execz .LBB0_192
	s_bcnt1_i32_b64 s8, s[8:9]
	v_mov_b32_e32 v4, 0x3f52f000
	v_mov_b32_e32 v5, s8
	global_atomic_add v4, v4, v5, s[30:31] offset:1024 sc0

; __device__ __forceinline__ unsigned xb_ld(unsigned* p)              { return __hip_atomic_load(p, __ATOMIC_RELAXED, __HIP_MEMORY_SCOPE_AGENT); }
; __device__ __forceinline__ unsigned xb_add(unsigned* p, unsigned v) { return __hip_atomic_fetch_add(p, v, __ATOMIC_RELAXED, __HIP_MEMORY_SCOPE_AGENT); }
; #define XB_SPIN(cond, bar) do { unsigned _sp = 0; while (cond) { __builtin_amdgcn_s_sleep(1); \
;     if ((++_sp & 255u) == 0u) { if (xb_ld(&(bar)[XB_TMO])) break; if (_sp > XB_SPIN_CAP) { atomicAdd(&(bar)[XB_TMO], 1u); break; } } } } while (0)
; __device__ __forceinline__ void xcd_barrier(const XcdBarrier& b) {
;     ...
;         if (old + 1u == (gen + 1u) * nloc) {
;             __builtin_amdgcn_fence(__ATOMIC_RELEASE, "agent");
;             asm volatile("s_waitcnt vmcnt(0)" ::: "memory");
;             const unsigned og = xb_add(&bar[XB_TOP], 1u);
;             const unsigned tg = og / nx;
;             if (og + 1u == (tg + 1u) * nx) xb_add(&bar[XB_TOPGEN], 1u);
;             else XB_SPIN(xb_ld(&bar[XB_TOPGEN]) == tg, bar);
;             __builtin_amdgcn_fence(__ATOMIC_ACQUIRE, "agent");
;             xb_add(&bar[XB_XGEN(b.x)], 1u);
.LBB0_322:
	s_andn2_saveexec_b64 s[6:7], s[6:7]
	s_cbranch_execz .LBB0_340
	s_mov_b64 s[6:7], exec
	buffer_wbl2 sc1
	buffer_inv sc1
	s_waitcnt lgkmcnt(0)
	s_waitcnt vmcnt(0)
	v_mbcnt_lo_u32_b32 v3, s6, 0
	v_mbcnt_hi_u32_b32 v3, s7, v3
	v_cmp_eq_u32_e32 vcc, 0, v3
	s_and_saveexec_b64 s[10:11], vcc
	s_cbranch_execz .LBB0_325
	s_bcnt1_i32_b64 s6, s[6:7]
	v_mov_b32_e32 v4, 0x3f52f000
	v_mov_b32_e32 v5, s6
	global_atomic_add v4, v4, v5, s[30:31] offset:1024 sc0

; __device__ __forceinline__ unsigned xb_ld(unsigned* p)              { return __hip_atomic_load(p, __ATOMIC_RELAXED, __HIP_MEMORY_SCOPE_AGENT); }
; __device__ __forceinline__ unsigned xb_add(unsigned* p, unsigned v) { return __hip_atomic_fetch_add(p, v, __ATOMIC_RELAXED, __HIP_MEMORY_SCOPE_AGENT); }
; #define XB_SPIN(cond, bar) do { unsigned _sp = 0; while (cond) { __builtin_amdgcn_s_sleep(1); \
;     if ((++_sp & 255u) == 0u) { if (xb_ld(&(bar)[XB_TMO])) break; if (_sp > XB_SPIN_CAP) { atomicAdd(&(bar)[XB_TMO], 1u); break; } } } } while (0)
; __device__ __forceinline__ void xcd_barrier(const XcdBarrier& b) {
;     ...
;         if (old + 1u == (gen + 1u) * nloc) {
;             __builtin_amdgcn_fence(__ATOMIC_RELEASE, "agent");
;             asm volatile("s_waitcnt vmcnt(0)" ::: "memory");
;             const unsigned og = xb_add(&bar[XB_TOP], 1u);
;             const unsigned tg = og / nx;
;             if (og + 1u == (tg + 1u) * nx) xb_add(&bar[XB_TOPGEN], 1u);
;             else XB_SPIN(xb_ld(&bar[XB_TOPGEN]) == tg, bar);
;             __builtin_amdgcn_fence(__ATOMIC_ACQUIRE, "agent");
;             xb_add(&bar[XB_XGEN(b.x)], 1u);
.LBB0_720:
	s_andn2_saveexec_b64 s[6:7], s[6:7]
	s_cbranch_execz .LBB0_738
	s_mov_b64 s[6:7], exec
	buffer_wbl2 sc1
	buffer_inv sc1
	s_waitcnt lgkmcnt(0)
	s_waitcnt vmcnt(0)
	v_mbcnt_lo_u32_b32 v3, s6, 0
	v_mbcnt_hi_u32_b32 v3, s7, v3
	v_cmp_eq_u32_e32 vcc, 0, v3
	s_and_saveexec_b64 s[8:9], vcc
	s_cbranch_execz .LBB0_723
	s_bcnt1_i32_b64 s6, s[6:7]
	v_mov_b32_e32 v4, 0x3f52f000
	v_mov_b32_e32 v5, s6
	global_atomic_add v4, v4, v5, s[30:31] offset:1024 sc0

; __device__ __forceinline__ unsigned xb_ld(unsigned* p)              { return __hip_atomic_load(p, __ATOMIC_RELAXED, __HIP_MEMORY_SCOPE_AGENT); }
; __device__ __forceinline__ unsigned xb_add(unsigned* p, unsigned v) { return __hip_atomic_fetch_add(p, v, __ATOMIC_RELAXED, __HIP_MEMORY_SCOPE_AGENT); }
; #define XB_SPIN(cond, bar) do { unsigned _sp = 0; while (cond) { __builtin_amdgcn_s_sleep(1); \
;     if ((++_sp & 255u) == 0u) { if (xb_ld(&(bar)[XB_TMO])) break; if (_sp > XB_SPIN_CAP) { atomicAdd(&(bar)[XB_TMO], 1u); break; } } } } while (0)
; __device__ __forceinline__ void xcd_barrier(const XcdBarrier& b) {
;     ...
;         if (old + 1u == (gen + 1u) * nloc) {
;             __builtin_amdgcn_fence(__ATOMIC_RELEASE, "agent");
;             asm volatile("s_waitcnt vmcnt(0)" ::: "memory");
;             const unsigned og = xb_add(&bar[XB_TOP], 1u);
;             const unsigned tg = og / nx;
;             if (og + 1u == (tg + 1u) * nx) xb_add(&bar[XB_TOPGEN], 1u);
;             else XB_SPIN(xb_ld(&bar[XB_TOPGEN]) == tg, bar);
;             __builtin_amdgcn_fence(__ATOMIC_ACQUIRE, "agent");
;             xb_add(&bar[XB_XGEN(b.x)], 1u);
.LBB0_2276:
	s_andn2_saveexec_b64 s[4:5], s[4:5]
	s_cbranch_execz .LBB0_2294
	s_mov_b64 s[4:5], exec
	buffer_wbl2 sc1
	buffer_inv sc1
	s_waitcnt lgkmcnt(0)
	s_waitcnt vmcnt(0)
	v_mbcnt_lo_u32_b32 v3, s4, 0
	v_mbcnt_hi_u32_b32 v3, s5, v3
	v_cmp_eq_u32_e32 vcc, 0, v3
	s_and_saveexec_b64 s[8:9], vcc
	s_cbranch_execz .LBB0_2279
	s_bcnt1_i32_b64 s4, s[4:5]
	v_mov_b32_e32 v4, 0x3f52f000
	v_mov_b32_e32 v5, s4
	global_atomic_add v4, v4, v5, s[30:31] offset:1024 sc0
